# GEMM1: next unit's K-tile-1 A(1,1) DMA hoisted above the epilogue stores, third counted wait of the following unit relaxed (one more SP of store drain)
# speedup vs baseline: 1.0073x; 1.0015x over previous
; #define PG8_STAGE(bufoff, gbase, voff) do { _Pragma("unroll") for (int _i = 0; _i < 2; ++_i) \
;         __builtin_amdgcn_global_load_lds((const unsigned*)((const char*)(gbase) + (voff)[_i]), (PG8_LAS unsigned*)(lds + (bufoff) + ldsw + _i * 8192), 16, 0, 0); } while (0)
; #define PG8_WAIT_V(n) asm volatile("s_waitcnt vmcnt(" #n ")" ::: "memory")
; #define PG8_BAR __builtin_amdgcn_s_barrier()
; template <class Epi, class Sched, bool ALIGN_EPI = false, bool SP2 = false>
; __device__ __forceinline__ void gemm_phase(PG8_LAS unsigned char* lds, const Gemm g, const Sched& S, const Epi& E) {
;     ...
;     if constexpr (SP2) {
;         PG8_STAGE(PG8_SB(0, 0), cB, voffB); PG8_STAGE(PG8_SB(0, 1), cB + hstep, voffB); PG8_STAGE(PG8_SA(0, 0), cA, voffA); PG8_STAGE(PG8_SA(0, 1), cA + hstep, voffA);
;         if (wr == 1) PG8_BAR;
;         PG8_WAIT_V(2); PG8_BAR;
;         PG8_STAGE(PG8_SB(1, 0), cB + kstep, voffB); PG8_STAGE(PG8_SA(1, 0), cA + kstep, voffA); PG8_STAGE(PG8_SB(1, 1), cB + hstep + kstep, voffB);
;         PG8_WAIT_V(6); PG8_BAR;
;     } else {
.LBB0_345:
	s_mov_b64 s[20:21], 0x80
	s_add_i32 m0, s59, 0x18000
	v_lshl_add_u64 v[8:9], v[8:9], 0, s[20:21]
	s_waitcnt vmcnt(2)
	s_barrier
	global_load_lds_dwordx4 v[8:9], off
	v_lshl_add_u64 v[4:5], v[4:5], 0, s[20:21]
	s_add_i32 m0, s59, 0x1a000
	s_add_i32 s63, s59, 0x8000
	global_load_lds_dwordx4 v[4:5], off
	v_lshl_add_u64 v[4:5], v[6:7], 0, s[20:21]
	s_mov_b32 m0, s63
	s_add_i32 s64, s59, 0xa000
	global_load_lds_dwordx4 v[4:5], off
	v_lshl_add_u64 v[4:5], v[10:11], 0, s[20:21]
	s_mov_b32 m0, s64
	v_lshl_add_u64 v[2:3], v[2:3], 0, s[20:21]
	global_load_lds_dwordx4 v[4:5], off
	s_add_i32 m0, s59, 0x1c000
	v_lshl_add_u64 v[0:1], v[0:1], 0, s[20:21]
	global_load_lds_dwordx4 v[2:3], off
	s_add_i32 m0, s59, 0x1e000
	s_lshr_b32 s1, s1, 26
	global_load_lds_dwordx4 v[0:1], off
	s_and_b32 s2, s2, 3
	s_add_i32 s1, s0, s1
	s_ashr_i32 s65, s1, 6
	s_lshl_b32 s66, s3, 6
	s_lshl_b32 s1, s3, 13
	s_lshl_b32 s67, s2, 5
	s_cmp_gt_i32 s0, 63
	s_cselect_b64 s[22:23], -1, 0
	s_add_i32 s68, s65, -2
	s_cmpk_lt_u32 s11, 0x100
	s_cselect_b64 s[24:25], -1, 0
	s_add_u32 s69, s90, 0x9000000
	s_addc_u32 s70, s91, 0
	s_add_u32 s26, s90, 0x2600000
	s_addc_u32 s27, s91, 0
	s_add_u32 s28, s90, 0x3e00000
	s_addc_u32 s29, s91, 0
	s_add_u32 s30, s90, 0x2200000
	s_addc_u32 s31, s91, 0
	v_lshlrev_b32_e32 v1, 2, v201
	s_add_u32 s71, s88, 0x4000000
	v_lshl_or_b32 v0, v201, 6, v238
	v_and_b32_e32 v1, 32, v1
	s_addc_u32 s72, s89, 0
	v_bitop3_b32 v0, v0, s1, v1 bitop3:0xde
	s_add_u32 s34, s90, 0x20000
	v_add_u32_e32 v1, v237, v235
	s_addc_u32 s35, s91, 0
	v_mul_lo_u32 v1, s0, v1
	s_add_u32 s36, s90, 0x100000
	v_lshlrev_b32_e32 v1, 1, v1
	s_addc_u32 s37, s91, 0
	v_add3_u32 v136, v233, v1, v234
	v_add_u32_e32 v1, v236, v235
	s_cmp_gt_u32 s2, 1
	v_mul_lo_u32 v1, s0, v1
	s_waitcnt vmcnt(6)
	s_cselect_b64 s[38:39], -1, 0
	s_cmp_eq_u32 s2, 2
	v_lshlrev_b32_e32 v1, 1, v1
	v_lshl_or_b32 v170, s2, 12, v239
	s_cselect_b64 s[40:41], -1, 0
	v_lshl_add_u64 v[138:139], s[12:13], 0, v[136:137]
	v_add3_u32 v136, v233, v1, v234
	s_add_i32 s75, 0, 0x10000
	s_add_i32 s76, 0, 0x14000
	v_add_u32_e32 v173, 0, v0
	v_mbcnt_lo_u32_b32 v0, -1, 0
	s_ashr_i32 s73, s83, 31
	s_mov_b32 s86, s80
	s_ashr_i32 s74, s80, 31
	v_lshl_add_u64 v[140:141], s[12:13], 0, v[136:137]
	v_mov_b64_e32 v[142:143], 0xb80
	v_mov_b64_e32 v[144:145], 0xb7f
	v_add_u32_e32 v171, s75, v170
	v_add_u32_e32 v172, s76, v170
	s_movk_i32 s77, 0x300
	s_mov_b64 s[42:43], 0xcffe200
	s_mov_b32 s78, 0xcffe000
	v_mbcnt_hi_u32_b32 v174, -1, v0
	s_mov_b32 s79, 0
	s_barrier
	s_mov_b32 s100, 0
	s_mov_b32 s99, 0
	s_branch .LBB0_348

; #define PG8_STAGE(bufoff, gbase, voff) do { _Pragma("unroll") for (int _i = 0; _i < 2; ++_i) \
;         __builtin_amdgcn_global_load_lds((const unsigned*)((const char*)(gbase) + (voff)[_i]), (PG8_LAS unsigned*)(lds + (bufoff) + ldsw + _i * 8192), 16, 0, 0); } while (0)
; #define PG8_LDA(dst, b, h) do { _Pragma("unroll") for (int m = 0; m < 4; ++m) _Pragma("unroll") for (int k = 0; k < 2; ++k) dst[m][k] = *(const PG8_LAS bf16x8*)(lds + PG8_SA(b, h) + aoff + m * 2048 + k * 1024); } while (0)
; #define PG8_LDB(dst, b, h) do { _Pragma("unroll") for (int n = 0; n < 2; ++n) _Pragma("unroll") for (int k = 0; k < 2; ++k) dst[n][k] = *(const PG8_LAS bf16x8*)(lds + PG8_SB(b, h) + boff + n * 2048 + k * 1024); } while (0)
; #define PG8_SCHED __builtin_amdgcn_sched_barrier(0)
; template <class Epi, class Sched, bool ALIGN_EPI = false, bool SP2 = false>
; __device__ __forceinline__ void gemm_phase(PG8_LAS unsigned char* lds, const Gemm g, const Sched& S, const Epi& E) {
;     ...
;             const bool last = (t == nt - 2);
;             const char* a1 = cA + (size_t)(t + 1) * kstep;
;             const char* a2 = last ? nA : cA + (size_t)(t + 2) * kstep; const char* b2 = last ? nB : cB + (size_t)(t + 2) * kstep;
;             const char* a3 = a2 + kstep; const char* b3 = b2 + kstep;
;             if (last && has_next) S.a_ready(nxt);
;             if constexpr (SP2) {
;             PG8_LDB(B0, 0, 0); PG8_LDB(B1, 0, 1); PG8_SCHED; PG8_LDA(At, 0, 0); PG8_STAGE(PG8_SA(1, 1), a1 + hstep, voffA);
.LBB0_354:
	s_andn2_b64 vcc, exec, s[22:23]
	s_waitcnt lgkmcnt(0)
	s_cbranch_vccnz .LBB0_357
	s_add_u32 s4, s4, 0x80
	s_addc_u32 s5, s5, 0
	s_add_u32 s11, s6, 0x100
	s_addc_u32 s16, s7, 0
	s_mov_b32 s6, 0
	ds_read_b128 v[146:149], v171
	ds_read_b128 v[150:153], v171 offset:1024
	ds_read_b128 v[154:157], v171 offset:2048
	ds_read_b128 v[158:161], v171 offset:3072
	ds_read_b128 v[162:165], v172
	ds_read_b128 v[166:169], v172 offset:1024
	ds_read_b128 v[176:179], v172 offset:2048
	ds_read_b128 v[180:183], v172 offset:3072
	s_add_i32 s46, s6, 2
	s_add_u32 s47, s4, 0x80
	s_addc_u32 s7, s5, 0
	s_cmp_eq_u32 s68, s6
	s_cselect_b32 s6, s0, s47
	s_cselect_b32 s7, s1, s7
	s_cselect_b32 s49, s45, s16
	s_cselect_b32 s48, s44, s11
	v_lshl_add_u64 v[218:219], s[4:5], 0, v[138:139]
	s_add_i32 m0, s59, 0xc000
	ds_read_b128 v[184:187], v173
	ds_read_b128 v[188:191], v173 offset:1024
	ds_read_b128 v[192:195], v173 offset:2048
	ds_read_b128 v[196:199], v173 offset:3072
	ds_read_b128 v[202:205], v173 offset:4096
	ds_read_b128 v[206:209], v173 offset:5120
	ds_read_b128 v[210:213], v173 offset:6144
	ds_read_b128 v[214:217], v173 offset:7168
	s_cmp_lg_u32 s100, 0
	s_cbranch_scc1 .Ly1_skip
	global_load_lds_dwordx4 v[218:219], off
	v_lshl_add_u64 v[218:219], s[4:5], 0, v[140:141]
	s_add_i32 m0, s59, 0xe000
	s_nop 0
	global_load_lds_dwordx4 v[218:219], off
.Ly1_skip:
	s_cmp_eq_u32 s99, 0
	s_cbranch_scc1 .Lw8_0_0
	s_waitcnt vmcnt(16)
	s_branch .Lwj_0_0

; #define PG8_STAGE(bufoff, gbase, voff) do { _Pragma("unroll") for (int _i = 0; _i < 2; ++_i) \
;         __builtin_amdgcn_global_load_lds((const unsigned*)((const char*)(gbase) + (voff)[_i]), (PG8_LAS unsigned*)(lds + (bufoff) + ldsw + _i * 8192), 16, 0, 0); } while (0)
; #define PG8_LDA(dst, b, h) do { _Pragma("unroll") for (int m = 0; m < 4; ++m) _Pragma("unroll") for (int k = 0; k < 2; ++k) dst[m][k] = *(const PG8_LAS bf16x8*)(lds + PG8_SA(b, h) + aoff + m * 2048 + k * 1024); } while (0)
; #define PG8_LDB(dst, b, h) do { _Pragma("unroll") for (int n = 0; n < 2; ++n) _Pragma("unroll") for (int k = 0; k < 2; ++k) dst[n][k] = *(const PG8_LAS bf16x8*)(lds + PG8_SB(b, h) + boff + n * 2048 + k * 1024); } while (0)
; #define PG8_MMA(ai, bj, At, Bt) do { __builtin_amdgcn_s_setprio(1); _Pragma("unroll") for (int m = 0; m < 4; ++m) _Pragma("unroll") for (int n = 0; n < 2; ++n) _Pragma("unroll") for (int k = 0; k < 2; ++k) \
;         acc[ai][bj][m][n] = __builtin_amdgcn_mfma_f32_16x16x32_bf16(Bt[n][k], At[m][k], acc[ai][bj][m][n], 0, 0, 0); __builtin_amdgcn_s_setprio(0); } while (0)
; #define PG8_WAIT_V(n) asm volatile("s_waitcnt vmcnt(" #n ")" ::: "memory")
; #define PG8_WAIT_L(n) asm volatile("s_waitcnt lgkmcnt(" #n ")" ::: "memory")
; #define PG8_BAR __builtin_amdgcn_s_barrier()
; #define PG8_SCHED __builtin_amdgcn_sched_barrier(0)
; template <class Epi, class Sched, bool ALIGN_EPI = false, bool SP2 = false>
; __device__ __forceinline__ void gemm_phase(PG8_LAS unsigned char* lds, const Gemm g, const Sched& S, const Epi& E) {
;     ...
;             PG8_WAIT_V(8); PG8_WAIT_L(0); PG8_BAR; PG8_MMA(0, 0, At, B0); PG8_MMA(0, 1, At, B1); PG8_BAR; PG8_SCHED;
;             PG8_LDA(At, 0, 1); PG8_STAGE(PG8_SB(0, 0), b2, voffB); PG8_STAGE(PG8_SB(0, 1), b2 + hstep, voffB); PG8_STAGE(PG8_SA(0, 0), a2, voffA);
;             PG8_WAIT_V(8); PG8_WAIT_L(0); PG8_BAR; PG8_MMA(1, 0, At, B0); PG8_MMA(1, 1, At, B1); PG8_BAR; PG8_SCHED;
;             PG8_LDB(B0, 1, 0); PG8_LDB(B1, 1, 1); PG8_SCHED; PG8_LDA(At, 1, 0); PG8_STAGE(PG8_SA(0, 1), a2 + hstep, voffA);
;             PG8_WAIT_V(8); PG8_WAIT_L(0); PG8_BAR; PG8_MMA(0, 0, At, B0); PG8_MMA(0, 1, At, B1); PG8_BAR; PG8_SCHED;
.Lwj_0_1:
	s_waitcnt lgkmcnt(0)
	s_barrier
	s_setprio 1
	s_waitcnt lgkmcnt(0)
	v_mfma_f32_16x16x32_bf16 v[60:63], v[146:149], v[184:187], 0
	v_mfma_f32_16x16x32_bf16 v[52:55], v[154:157], v[184:187], 0
	v_mfma_f32_16x16x32_bf16 v[44:47], v[146:149], v[192:195], 0
	v_mfma_f32_16x16x32_bf16 v[36:39], v[154:157], v[192:195], 0
	v_mfma_f32_16x16x32_bf16 v[28:31], v[146:149], v[202:205], 0
	v_mfma_f32_16x16x32_bf16 v[20:23], v[154:157], v[202:205], 0
	v_mfma_f32_16x16x32_bf16 v[12:15], v[146:149], v[210:213], 0
	v_mfma_f32_16x16x32_bf16 v[4:7], v[154:157], v[210:213], 0
	v_mfma_f32_16x16x32_bf16 v[60:63], v[150:153], v[188:191], v[60:63]
	v_mfma_f32_16x16x32_bf16 v[52:55], v[158:161], v[188:191], v[52:55]
	v_mfma_f32_16x16x32_bf16 v[44:47], v[150:153], v[196:199], v[44:47]
	v_mfma_f32_16x16x32_bf16 v[36:39], v[158:161], v[196:199], v[36:39]
	v_mfma_f32_16x16x32_bf16 v[28:31], v[150:153], v[206:209], v[28:31]
	v_mfma_f32_16x16x32_bf16 v[20:23], v[158:161], v[206:209], v[20:23]
	v_mfma_f32_16x16x32_bf16 v[12:15], v[150:153], v[214:217], v[12:15]
	v_mfma_f32_16x16x32_bf16 v[4:7], v[158:161], v[214:217], v[4:7]
	s_setprio 0
	s_setprio 1
	v_mfma_f32_16x16x32_bf16 v[56:59], v[162:165], v[184:187], 0
	v_mfma_f32_16x16x32_bf16 v[48:51], v[176:179], v[184:187], 0
	v_mfma_f32_16x16x32_bf16 v[40:43], v[162:165], v[192:195], 0
	v_mfma_f32_16x16x32_bf16 v[32:35], v[176:179], v[192:195], 0
	v_mfma_f32_16x16x32_bf16 v[24:27], v[162:165], v[202:205], 0
	v_mfma_f32_16x16x32_bf16 v[16:19], v[176:179], v[202:205], 0
	v_mfma_f32_16x16x32_bf16 v[8:11], v[162:165], v[210:213], 0
	v_mfma_f32_16x16x32_bf16 v[0:3], v[176:179], v[210:213], 0
	v_mfma_f32_16x16x32_bf16 v[56:59], v[166:169], v[188:191], v[56:59]
	v_mfma_f32_16x16x32_bf16 v[48:51], v[180:183], v[188:191], v[48:51]
	v_mfma_f32_16x16x32_bf16 v[40:43], v[166:169], v[196:199], v[40:43]
	v_mfma_f32_16x16x32_bf16 v[32:35], v[180:183], v[196:199], v[32:35]
	v_mfma_f32_16x16x32_bf16 v[24:27], v[166:169], v[206:209], v[24:27]
	v_mfma_f32_16x16x32_bf16 v[16:19], v[180:183], v[206:209], v[16:19]
	v_mfma_f32_16x16x32_bf16 v[8:11], v[166:169], v[214:217], v[8:11]
	v_mfma_f32_16x16x32_bf16 v[0:3], v[180:183], v[214:217], v[0:3]
	s_setprio 0
	s_barrier
	s_add_i32 s47, 0, 0x18000
	v_add_u32_e32 v136, s47, v170
	s_add_i32 s48, 0, 0x1c000
	ds_read_b128 v[146:149], v136
	ds_read_b128 v[150:153], v136 offset:1024
	ds_read_b128 v[154:157], v136 offset:2048
	ds_read_b128 v[158:161], v136 offset:3072
	v_add_u32_e32 v136, s48, v170
	ds_read_b128 v[162:165], v136
	ds_read_b128 v[166:169], v136 offset:1024
	ds_read_b128 v[176:179], v136 offset:2048
	ds_read_b128 v[180:183], v136 offset:3072
	s_add_u32 s6, s6, s12
	s_addc_u32 s7, s7, s13
	s_mov_b32 m0, s61
	v_lshl_add_u64 v[230:231], s[6:7], 0, v[128:129]
	ds_read_b128 v[184:187], v173 offset:32768
	ds_read_b128 v[188:191], v173 offset:33792
	ds_read_b128 v[192:195], v173 offset:34816
	ds_read_b128 v[196:199], v173 offset:35840
	ds_read_b128 v[202:205], v173 offset:36864
	ds_read_b128 v[206:209], v173 offset:37888
	ds_read_b128 v[210:213], v173 offset:38912
	ds_read_b128 v[214:217], v173 offset:39936
	global_load_lds_dwordx4 v[230:231], off
	v_lshl_add_u64 v[230:231], s[6:7], 0, v[132:133]
	s_mov_b32 m0, s62
	s_nop 0
	global_load_lds_dwordx4 v[230:231], off
	s_cmp_eq_u32 s99, 0
	s_cbranch_scc1 .Lw8_0_2
	s_waitcnt vmcnt(16)
	s_branch .Lwj_0_2

; #define PG8_STAGE(bufoff, gbase, voff) do { _Pragma("unroll") for (int _i = 0; _i < 2; ++_i) \
;         __builtin_amdgcn_global_load_lds((const unsigned*)((const char*)(gbase) + (voff)[_i]), (PG8_LAS unsigned*)(lds + (bufoff) + ldsw + _i * 8192), 16, 0, 0); } while (0)
; #define PG8_LDA(dst, b, h) do { _Pragma("unroll") for (int m = 0; m < 4; ++m) _Pragma("unroll") for (int k = 0; k < 2; ++k) dst[m][k] = *(const PG8_LAS bf16x8*)(lds + PG8_SA(b, h) + aoff + m * 2048 + k * 1024); } while (0)
; #define PG8_LDB(dst, b, h) do { _Pragma("unroll") for (int n = 0; n < 2; ++n) _Pragma("unroll") for (int k = 0; k < 2; ++k) dst[n][k] = *(const PG8_LAS bf16x8*)(lds + PG8_SB(b, h) + boff + n * 2048 + k * 1024); } while (0)
; #define PG8_MMA(ai, bj, At, Bt) do { __builtin_amdgcn_s_setprio(1); _Pragma("unroll") for (int m = 0; m < 4; ++m) _Pragma("unroll") for (int n = 0; n < 2; ++n) _Pragma("unroll") for (int k = 0; k < 2; ++k) \
;         acc[ai][bj][m][n] = __builtin_amdgcn_mfma_f32_16x16x32_bf16(Bt[n][k], At[m][k], acc[ai][bj][m][n], 0, 0, 0); __builtin_amdgcn_s_setprio(0); } while (0)
; #define PG8_WAIT_V(n) asm volatile("s_waitcnt vmcnt(" #n ")" ::: "memory")
; #define PG8_WAIT_L(n) asm volatile("s_waitcnt lgkmcnt(" #n ")" ::: "memory")
; #define PG8_BAR __builtin_amdgcn_s_barrier()
; #define PG8_SCHED __builtin_amdgcn_sched_barrier(0)
; template <class Epi, class Sched, bool ALIGN_EPI = false, bool SP2 = false>
; __device__ __forceinline__ void gemm_phase(PG8_LAS unsigned char* lds, const Gemm g, const Sched& S, const Epi& E) {
;     ...
;             PG8_WAIT_V(8); PG8_WAIT_L(0); PG8_BAR; PG8_MMA(1, 0, At, B0); PG8_MMA(1, 1, At, B1); PG8_BAR; PG8_SCHED;
;             PG8_LDB(B0, 1, 0); PG8_LDB(B1, 1, 1); PG8_SCHED; PG8_LDA(At, 1, 0); PG8_STAGE(PG8_SA(0, 1), a2 + hstep, voffA);
;             PG8_WAIT_V(8); PG8_WAIT_L(0); PG8_BAR; PG8_MMA(0, 0, At, B0); PG8_MMA(0, 1, At, B1); PG8_BAR; PG8_SCHED;
;             PG8_LDA(At, 1, 1); PG8_STAGE(PG8_SB(1, 0), b3, voffB); PG8_STAGE(PG8_SB(1, 1), b3 + hstep, voffB); PG8_STAGE(PG8_SA(1, 0), a3, voffA);
;             PG8_WAIT_V(8); PG8_WAIT_L(0); PG8_BAR; PG8_MMA(1, 0, At, B0); PG8_MMA(1, 1, At, B1); PG8_BAR; PG8_SCHED;
.Lwj_0_2:
	s_waitcnt lgkmcnt(0)
	s_barrier
	s_setprio 1
	s_waitcnt lgkmcnt(0)
	v_mfma_f32_16x16x32_bf16 v[120:123], v[146:149], v[184:187], v[120:123]
	v_mfma_f32_16x16x32_bf16 v[116:119], v[154:157], v[184:187], v[116:119]
	v_mfma_f32_16x16x32_bf16 v[108:111], v[146:149], v[192:195], v[108:111]
	v_mfma_f32_16x16x32_bf16 v[100:103], v[154:157], v[192:195], v[100:103]
	v_mfma_f32_16x16x32_bf16 v[92:95], v[146:149], v[202:205], v[92:95]
	v_mfma_f32_16x16x32_bf16 v[84:87], v[154:157], v[202:205], v[84:87]
	v_mfma_f32_16x16x32_bf16 v[76:79], v[146:149], v[210:213], v[76:79]
	v_mfma_f32_16x16x32_bf16 v[68:71], v[154:157], v[210:213], v[68:71]
	v_mfma_f32_16x16x32_bf16 v[120:123], v[150:153], v[188:191], v[120:123]
	v_mfma_f32_16x16x32_bf16 v[116:119], v[158:161], v[188:191], v[116:119]
	v_mfma_f32_16x16x32_bf16 v[108:111], v[150:153], v[196:199], v[108:111]
	v_mfma_f32_16x16x32_bf16 v[100:103], v[158:161], v[196:199], v[100:103]
	v_mfma_f32_16x16x32_bf16 v[92:95], v[150:153], v[206:209], v[92:95]
	v_mfma_f32_16x16x32_bf16 v[84:87], v[158:161], v[206:209], v[84:87]
	v_mfma_f32_16x16x32_bf16 v[76:79], v[150:153], v[214:217], v[76:79]
	v_mfma_f32_16x16x32_bf16 v[68:71], v[158:161], v[214:217], v[68:71]
	s_setprio 0
	s_setprio 1
	v_mfma_f32_16x16x32_bf16 v[124:127], v[162:165], v[184:187], v[124:127]
	v_mfma_f32_16x16x32_bf16 v[112:115], v[176:179], v[184:187], v[112:115]
	v_mfma_f32_16x16x32_bf16 v[104:107], v[162:165], v[192:195], v[104:107]
	v_mfma_f32_16x16x32_bf16 v[96:99], v[176:179], v[192:195], v[96:99]
	v_mfma_f32_16x16x32_bf16 v[88:91], v[162:165], v[202:205], v[88:91]
	v_mfma_f32_16x16x32_bf16 v[80:83], v[176:179], v[202:205], v[80:83]
	v_mfma_f32_16x16x32_bf16 v[72:75], v[162:165], v[210:213], v[72:75]
	v_mfma_f32_16x16x32_bf16 v[64:67], v[176:179], v[210:213], v[64:67]
	v_mfma_f32_16x16x32_bf16 v[124:127], v[166:169], v[188:191], v[124:127]
	v_mfma_f32_16x16x32_bf16 v[112:115], v[180:183], v[188:191], v[112:115]
	v_mfma_f32_16x16x32_bf16 v[104:107], v[166:169], v[196:199], v[104:107]
	v_mfma_f32_16x16x32_bf16 v[96:99], v[180:183], v[196:199], v[96:99]
	v_mfma_f32_16x16x32_bf16 v[88:91], v[166:169], v[206:209], v[88:91]
	v_mfma_f32_16x16x32_bf16 v[80:83], v[180:183], v[206:209], v[80:83]
	v_mfma_f32_16x16x32_bf16 v[72:75], v[166:169], v[214:217], v[72:75]
	v_mfma_f32_16x16x32_bf16 v[64:67], v[180:183], v[214:217], v[64:67]
	s_setprio 0
	s_barrier
	s_add_i32 s6, s47, s58
	v_lshl_add_u64 v[218:219], v[218:219], 0, s[20:21]
	s_mov_b32 m0, s6
	ds_read_b128 v[184:187], v173 offset:49152
	ds_read_b128 v[188:191], v173 offset:50176
	ds_read_b128 v[192:195], v173 offset:51200
	ds_read_b128 v[196:199], v173 offset:52224
	ds_read_b128 v[202:205], v173 offset:53248
	ds_read_b128 v[206:209], v173 offset:54272
	ds_read_b128 v[210:213], v173 offset:55296
	ds_read_b128 v[214:217], v173 offset:56320
	global_load_lds_dwordx4 v[218:219], off
	v_lshl_add_u64 v[218:219], v[220:221], 0, s[20:21]
	s_add_i32 m0, s6, 0x2000
	s_add_i32 s6, s48, s58
	global_load_lds_dwordx4 v[218:219], off
	v_lshl_add_u64 v[218:219], v[222:223], 0, s[20:21]
	s_mov_b32 m0, s6
	s_nop 0
	global_load_lds_dwordx4 v[218:219], off
	v_lshl_add_u64 v[218:219], v[224:225], 0, s[20:21]
	s_add_i32 m0, s6, 0x2000
	s_nop 0
	global_load_lds_dwordx4 v[218:219], off
	v_lshl_add_u64 v[218:219], v[226:227], 0, s[20:21]
	s_mov_b32 m0, s63
	s_nop 0
	global_load_lds_dwordx4 v[218:219], off
	v_lshl_add_u64 v[218:219], v[228:229], 0, s[20:21]
	s_mov_b32 m0, s64
	s_nop 0
	global_load_lds_dwordx4 v[218:219], off
	s_waitcnt vmcnt(8)
	s_waitcnt lgkmcnt(0)
	s_barrier
	s_setprio 1
	s_waitcnt lgkmcnt(0)
	v_mfma_f32_16x16x32_bf16 v[60:63], v[146:149], v[184:187], v[60:63]
	v_mfma_f32_16x16x32_bf16 v[52:55], v[154:157], v[184:187], v[52:55]
	v_mfma_f32_16x16x32_bf16 v[44:47], v[146:149], v[192:195], v[44:47]
	v_mfma_f32_16x16x32_bf16 v[36:39], v[154:157], v[192:195], v[36:39]
	v_mfma_f32_16x16x32_bf16 v[28:31], v[146:149], v[202:205], v[28:31]
	v_mfma_f32_16x16x32_bf16 v[20:23], v[154:157], v[202:205], v[20:23]
	v_mfma_f32_16x16x32_bf16 v[12:15], v[146:149], v[210:213], v[12:15]
	v_mfma_f32_16x16x32_bf16 v[4:7], v[154:157], v[210:213], v[4:7]
	v_mfma_f32_16x16x32_bf16 v[60:63], v[150:153], v[188:191], v[60:63]
	v_mfma_f32_16x16x32_bf16 v[52:55], v[158:161], v[188:191], v[52:55]
	v_mfma_f32_16x16x32_bf16 v[44:47], v[150:153], v[196:199], v[44:47]
	v_mfma_f32_16x16x32_bf16 v[36:39], v[158:161], v[196:199], v[36:39]
	v_mfma_f32_16x16x32_bf16 v[28:31], v[150:153], v[206:209], v[28:31]
	v_mfma_f32_16x16x32_bf16 v[20:23], v[158:161], v[206:209], v[20:23]
	v_mfma_f32_16x16x32_bf16 v[12:15], v[150:153], v[214:217], v[12:15]
	v_mfma_f32_16x16x32_bf16 v[4:7], v[158:161], v[214:217], v[4:7]
	s_setprio 0
	s_setprio 1
	v_mfma_f32_16x16x32_bf16 v[56:59], v[162:165], v[184:187], v[56:59]
	v_mfma_f32_16x16x32_bf16 v[48:51], v[176:179], v[184:187], v[48:51]
	v_mfma_f32_16x16x32_bf16 v[40:43], v[162:165], v[192:195], v[40:43]
	v_mfma_f32_16x16x32_bf16 v[32:35], v[176:179], v[192:195], v[32:35]
	v_mfma_f32_16x16x32_bf16 v[24:27], v[162:165], v[202:205], v[24:27]
	v_mfma_f32_16x16x32_bf16 v[16:19], v[176:179], v[202:205], v[16:19]
	v_mfma_f32_16x16x32_bf16 v[8:11], v[162:165], v[210:213], v[8:11]
	v_mfma_f32_16x16x32_bf16 v[0:3], v[176:179], v[210:213], v[0:3]
	v_mfma_f32_16x16x32_bf16 v[56:59], v[166:169], v[188:191], v[56:59]
	v_mfma_f32_16x16x32_bf16 v[48:51], v[180:183], v[188:191], v[48:51]
	v_mfma_f32_16x16x32_bf16 v[40:43], v[166:169], v[196:199], v[40:43]
	v_mfma_f32_16x16x32_bf16 v[32:35], v[180:183], v[196:199], v[32:35]
	v_mfma_f32_16x16x32_bf16 v[24:27], v[166:169], v[206:209], v[24:27]
	v_mfma_f32_16x16x32_bf16 v[16:19], v[180:183], v[206:209], v[16:19]
	v_mfma_f32_16x16x32_bf16 v[8:11], v[166:169], v[214:217], v[8:11]
	v_mfma_f32_16x16x32_bf16 v[0:3], v[180:183], v[214:217], v[0:3]
	s_setprio 0
	s_barrier
	s_add_u32 s4, s4, 0x100
	s_addc_u32 s5, s5, 0
	s_add_u32 s11, s11, 0x100
	s_addc_u32 s16, s16, 0
	s_cmp_ge_i32 s46, s65
	s_mov_b32 s6, s46
	s_cbranch_scc1 .LBB0_357

; template <class Epi, class Sched, bool ALIGN_EPI = false, bool SP2 = false>
; __device__ __forceinline__ void gemm_phase(PG8_LAS unsigned char* lds, const Gemm g, const Sched& S, const Epi& E) {
;     ...
;             const char* a1 = cA + (size_t)(t + 1) * kstep;
;             const char* a2 = last ? nA : cA + (size_t)(t + 2) * kstep; const char* b2 = last ? nB : cB + (size_t)(t + 2) * kstep;
;             const char* a3 = a2 + kstep; const char* b3 = b2 + kstep;
;     __device__ __forceinline__ void operator()(const AccT& acc, const Unit& u, int wr, int wc, int fr_, int fq_) const {
;         int fr = fr_, fq = fq_; asm volatile("" : "+v"(fr), "+v"(fq));
;         const int pn = u.pn < 8 ? u.pn : u.pn + 8, cb = wc * 32 + 8 * fq;
;         bf16_t* const U = (bf16_t*)(ws + WS_RB); bf16_t* const A2 = (bf16_t*)(ws + WS_A2); bf16_t* const QL = (bf16_t*)(ws + WS_QL); bf16_t* const KVL = (bf16_t*)(ws + WS_KVL); bf16_t* const KPE = (bf16_t*)(ws + WS_KPE);
;         bf16_t* const R = (bf16_t*)out; bf16_t* const SB = (bf16_t*)out + (size_t)T * 1024; float* const ssq_q = (float*)(ws + WS_SSQ); float* const ssq_kv = ssq_q + T; const float* const rope = (const float*)(ws + WS_ROPE);
; #pragma unroll
;         for (int ai = 0; ai < 2; ++ai)
; #pragma unroll
;             for (int m = 0; m < 4; ++m) {
;                 const size_t row = (size_t)ROW_OF(ai, m);
;                 const f32x4 a0 = acc[ai][0][m][0], a1 = acc[ai][0][m][1], b0 = acc[ai][1][m][0], b1 = acc[ai][1][m][1];
;                 if (pn < 8) {
.LBB0_359:
	s_add_u32 s4, s0, 0x80
	s_addc_u32 s5, s1, 0
	v_lshl_add_u64 v[218:219], s[4:5], 0, v[138:139]
	s_add_i32 m0, s59, 0xc000
	s_mov_b32 s100, 1
	global_load_lds_dwordx4 v[218:219], off
	v_lshl_add_u64 v[218:219], s[4:5], 0, v[140:141]
	s_add_i32 m0, s59, 0xe000
	s_nop 0
	global_load_lds_dwordx4 v[218:219], off
	s_add_i32 s4, s10, 8
	s_cmp_lt_i32 s10, 8
	s_cselect_b32 s82, s10, s4
	s_cmp_lg_u32 s82, 18
	s_cselect_b32 s99, 1, 0
	s_cmp_gt_i32 s82, 7
	s_cselect_b64 s[10:11], -1, 0
	s_cmp_gt_u32 s82, 22
	s_cselect_b64 s[48:49], -1, 0
	s_lshl_b32 s6, s82, 7
	s_add_i32 s16, s6, 0xfffff480
	s_lshl_b64 s[46:47], s[16:17], 1
	v_mov_b32_e32 v136, v201
	v_mov_b32_e32 v150, v232
	s_add_u32 s50, s88, s46
	s_addc_u32 s51, s89, s47
	v_lshl_add_u32 v148, v150, 3, s67
	v_lshlrev_b32_e32 v146, 4, v150
	v_ashrrev_i32_e32 v149, 31, v148
	s_add_u32 s46, s71, s46
	v_ashrrev_i32_e32 v147, 31, v146
	v_lshlrev_b64 v[160:161], 1, v[148:149]
	s_addc_u32 s47, s72, s47
	s_lshl_b32 s7, s82, 9
	v_lshl_add_u64 v[158:159], v[146:147], 2, s[36:37]
	v_lshlrev_b32_e32 v146, 8, v150
	v_cmp_eq_u32_e64 s[4:5], 0, v150
	v_lshl_add_u64 v[150:151], s[46:47], 0, v[160:161]
	s_add_u32 s46, s90, s7
	s_addc_u32 s47, s91, 0
	s_ashr_i32 s7, s6, 31
	s_lshl_b64 s[6:7], s[6:7], 1
	s_add_u32 s6, s69, s6
	s_addc_u32 s7, s70, s7
	s_lshl_b32 s16, s33, 8
	s_add_i32 s16, s16, s66
	v_and_b32_e32 v175, 0x100, v146
	v_and_b32_e32 v156, 0xfffffe00, v146
	v_add_u32_e32 v146, s16, v136
	v_ashrrev_i32_e32 v157, 31, v156
	v_lshl_add_u64 v[154:155], s[28:29], 0, v[160:161]
	v_lshl_add_u64 v[152:153], s[50:51], 0, v[160:161]
	v_ashrrev_i32_e32 v147, 31, v146
	s_mov_b64 s[50:51], -1
	s_and_b64 vcc, exec, s[10:11]
	s_cbranch_vccz .LBB0_391
	s_cmp_gt_u32 s82, 18
	s_cbranch_scc1 .LBB0_382
	s_mov_b64 s[54:55], -1
	s_mov_b64 s[50:51], 0
	s_cmp_lt_i32 s82, 17
	s_mov_b64 s[52:53], 0
	s_cbranch_scc0 .LBB0_364
	s_and_b64 vcc, exec, s[54:55]
	s_cbranch_vccnz .LBB0_381
